# post phase hoisted loads with store-inclusive counted waits (no per-segment wait on store acks)
# baseline (speedup 1.0000x reference)
; __device__ __forceinline__ float bf2f(unsigned h) { return __uint_as_float(h << 16); }
; __device__ __forceinline__ unsigned pk2(float lo, float hi) { f32x2 v = {lo, hi}; bf16x2_t b = __builtin_convertvector(v, bf16x2_t); return __builtin_bit_cast(unsigned, b); }
; __global__ void __launch_bounds__(512, 2) fwd_kernel(Params P) {
;     ...
;         for (int row = gw; row < MR; row += NGW) {
;             bf16_t* pr = BIG + (size_t)row * PROJ_LD;
;             const int pos = row_pos(row);
;             float cs[8], sn[8];
; #pragma unroll
;             for (int i = 0; i < 8; ++i) { const float inv = __builtin_amdgcn_exp2f(-(float)(dsub + i) * (13.287712379549449f / 32.0f)); const float ang_ = (float)pos * inv; sn[i] = __sinf(ang_); cs[i] = __cosf(ang_); }
;             { const u32x4 raw = *(const u32x4*)(pr + lane * 8); float x[8], y[8];
; #pragma unroll
;               for (int i = 0; i < 4; ++i) { x[2 * i] = bf2f(raw[i] & 0xffff); x[2 * i + 1] = bf2f(raw[i] >> 16); }
; #pragma unroll
;               for (int i = 0; i < 8; ++i) { const float o = __shfl_xor(x[i], 4); y[i] = (ishi ? (x[i] * cs[i] + o * sn[i]) : (x[i] * cs[i] - o * sn[i])) * (0.125f * LOG2E); }
;               u32x4 wv; wv.x = pk2(y[0], y[1]); wv.y = pk2(y[2], y[3]); wv.z = pk2(y[4], y[5]); wv.w = pk2(y[6], y[7]); *(u32x4*)(pr + lane * 8) = wv; }
;             { const u32x4 raw = *(const u32x4*)(pr + 512 + lane * 8); float x[8], y[8];
; #pragma unroll
;               for (int i = 0; i < 4; ++i) { x[2 * i] = bf2f(raw[i] & 0xffff); x[2 * i + 1] = bf2f(raw[i] >> 16); }
; #pragma unroll
;               for (int i = 0; i < 8; ++i) { const float o = __shfl_xor(x[i], 4); y[i] = ishi ? (x[i] * cs[i] + o * sn[i]) : (x[i] * cs[i] - o * sn[i]); }
;               float* fo = OUT + O_AK + (size_t)row * 512 + lane * 8; __builtin_nontemporal_store((f32x4){y[0], y[1], y[2], y[3]}, (f32x4*)fo); __builtin_nontemporal_store((f32x4){y[4], y[5], y[6], y[7]}, (f32x4*)(fo + 4));
;               u32x4 wv; wv.x = pk2(y[0], y[1]); wv.y = pk2(y[2], y[3]); wv.z = pk2(y[4], y[5]); wv.w = pk2(y[6], y[7]);
;               if (row < NP) *(u32x4*)(pr + 512 + lane * 8) = wv;
;               else { const int bs = (row - NP) >> 4, t = (row - NP) & 15; *(u32x4*)(KAS + ((size_t)bs * LKSP + 1024 + t) * 512 + lane * 8) = wv; } }
.LBB0_515:
	s_cmpk_gt_i32 s60, 0x7fff
	s_cselect_b64 s[14:15], -1, 0
	s_and_b32 s70, s60, 15
	s_and_b32 s3, s60, 0x7ff
	s_or_b32 s4, s70, 0x400
	s_cmp_lt_i32 s60, 0x8000
	s_cselect_b32 s3, s3, s4
	s_waitcnt lgkmcnt(7)
	v_cvt_f32_u32_e32 v0, s3
	s_mov_b32 s3, 0x8080000
	s_mov_b64 s[12:13], -1
	v_mul_f32_e32 v1, v58, v0
	v_mul_f32_e32 v1, 0.15915494, v1
	v_sin_f32_e32 v40, v1
	v_cos_f32_e32 v36, v1
	v_mul_f32_e32 v1, v59, v0
	v_mul_f32_e32 v1, 0.15915494, v1
	v_sin_f32_e32 v39, v1
	v_cos_f32_e32 v38, v1
	v_mul_f32_e32 v1, v60, v0
	v_mul_f32_e32 v1, 0.15915494, v1
	v_sin_f32_e32 v34, v1
	v_cos_f32_e32 v32, v1
	v_mul_f32_e32 v1, v61, v0
	v_mul_f32_e32 v1, 0.15915494, v1
	v_sin_f32_e32 v35, v1
	v_cos_f32_e32 v33, v1
	v_mul_f32_e32 v1, v62, v0
	v_mul_f32_e32 v1, 0.15915494, v1
	v_sin_f32_e32 v30, v1
	v_cos_f32_e32 v28, v1
	v_mul_f32_e32 v1, v63, v0
	v_mul_f32_e32 v1, 0.15915494, v1
	v_sin_f32_e32 v31, v1
	v_cos_f32_e32 v29, v1
	v_mul_f32_e32 v1, v64, v0
	v_mul_f32_e32 v0, v65, v0
	v_mul_f32_e32 v1, 0.15915494, v1
	v_mul_f32_e32 v0, 0.15915494, v0
	v_sin_f32_e32 v26, v1
	v_cos_f32_e32 v24, v1
	v_sin_f32_e32 v27, v0
	v_cos_f32_e32 v25, v0
	global_load_dwordx4 v[72:75], v[22:23], off
	global_load_dwordx4 v[76:79], v[22:23], off offset:1024
	global_load_dwordx4 v[82:85], v[22:23], off offset:2048
	v_mov_b32_e32 v86, 0
	v_mov_b32_e32 v87, 0
	v_mov_b32_e32 v88, 0
	v_mov_b32_e32 v89, 0
	v_mov_b32_e32 v90, 0
	v_mov_b32_e32 v91, 0
	v_mov_b32_e32 v92, 0
	v_mov_b32_e32 v93, 0
	v_mov_b32_e32 v94, 0
	v_mov_b32_e32 v95, 0
	v_mov_b32_e32 v96, 0
	v_mov_b32_e32 v97, 0
	s_mov_b32 s98, 0x1000
	s_mov_b32 s99, 0
	v_lshl_add_u64 v[104:105], v[22:23], 0, s[98:99]
	s_mov_b64 s[100:101], exec
	s_and_b64 exec, s[100:101], s[6:7]
	global_load_dwordx4 v[86:89], v[22:23], off offset:3072
	s_and_b64 exec, s[100:101], s[8:9]
	global_load_dwordx4 v[90:93], v[22:23], off offset:3840
	s_and_b64 exec, s[100:101], s[10:11]
	global_load_dwordx4 v[94:97], v[104:105], off offset:256
	s_mov_b64 exec, s[100:101]
	v_mov_b32_e32 v41, v39
	v_mov_b32_e32 v37, v38
	s_waitcnt vmcnt(5)
	s_nop 1
	v_mov_b32_e32 v0, v72
	v_mov_b32_e32 v1, v73
	v_mov_b32_e32 v2, v74
	v_mov_b32_e32 v3, v75
	v_lshlrev_b32_e32 v5, 16, v0
	v_and_b32_e32 v4, 0xffff0000, v0
	ds_bpermute_b32 v0, v52, v5
	s_waitcnt lgkmcnt(0)
	v_mul_f32_e32 v0, v40, v0
	v_cndmask_b32_e64 v6, v0, -v0, s[0:1]
	v_fmac_f32_e32 v6, v36, v5
	ds_bpermute_b32 v5, v52, v4
	s_waitcnt lgkmcnt(0)
	v_pk_mul_f32 v[4:5], v[38:39], v[4:5]
	s_nop 0
	v_add_f32_e32 v0, v4, v5
	v_sub_f32_e32 v4, v4, v5
	v_cndmask_b32_e64 v7, v0, v4, s[0:1]
	v_lshlrev_b32_e32 v0, 16, v1
	v_and_b32_e32 v1, 0xffff0000, v1
	v_pk_mul_f32 v[4:5], v[6:7], s[58:59] op_sel_hi:[1,0]
	ds_bpermute_b32 v6, v52, v0
	ds_bpermute_b32 v7, v52, v1
	s_waitcnt lgkmcnt(0)
	v_pk_mul_f32 v[6:7], v[34:35], v[6:7]
	s_nop 0
	v_pk_fma_f32 v[42:43], v[32:33], v[0:1], v[6:7]
	v_pk_fma_f32 v[0:1], v[32:33], v[0:1], v[6:7] neg_lo:[0,0,1] neg_hi:[0,0,1]
	s_nop 0
	v_cndmask_b32_e64 v1, v43, v1, s[0:1]
	v_cndmask_b32_e64 v0, v42, v0, s[0:1]
	v_pk_mul_f32 v[6:7], v[0:1], s[58:59] op_sel_hi:[1,0]
	v_lshlrev_b32_e32 v0, 16, v2
	v_and_b32_e32 v1, 0xffff0000, v2
	ds_bpermute_b32 v42, v52, v0
	ds_bpermute_b32 v43, v52, v1
	s_waitcnt lgkmcnt(0)
	v_pk_mul_f32 v[42:43], v[30:31], v[42:43]
	s_nop 0
	v_pk_fma_f32 v[44:45], v[28:29], v[0:1], v[42:43]
	v_pk_fma_f32 v[0:1], v[28:29], v[0:1], v[42:43] neg_lo:[0,0,1] neg_hi:[0,0,1]
	s_nop 0
	v_cndmask_b32_e64 v1, v45, v1, s[0:1]
	v_cndmask_b32_e64 v0, v44, v0, s[0:1]
	v_pk_mul_f32 v[42:43], v[0:1], s[58:59] op_sel_hi:[1,0]
	v_lshlrev_b32_e32 v0, 16, v3
	v_and_b32_e32 v1, 0xffff0000, v3
	ds_bpermute_b32 v2, v52, v0
	ds_bpermute_b32 v3, v52, v1
	s_waitcnt lgkmcnt(0)
	v_pk_mul_f32 v[2:3], v[26:27], v[2:3]
	s_nop 0
	v_pk_fma_f32 v[44:45], v[24:25], v[0:1], v[2:3]
	v_pk_fma_f32 v[0:1], v[24:25], v[0:1], v[2:3] neg_lo:[0,0,1] neg_hi:[0,0,1]
	v_cvt_pk_bf16_f32 v2, v42, v43
	v_cndmask_b32_e64 v1, v45, v1, s[0:1]
	v_cndmask_b32_e64 v0, v44, v0, s[0:1]
	v_pk_mul_f32 v[44:45], v[0:1], s[58:59] op_sel_hi:[1,0]
	v_cvt_pk_bf16_f32 v0, v4, v5
	v_cvt_pk_bf16_f32 v1, v6, v7
	v_cvt_pk_bf16_f32 v3, v44, v45
	global_store_dwordx4 v[22:23], v[0:3], off
	s_waitcnt vmcnt(5)
	s_nop 1
	v_mov_b32_e32 v0, v76
	v_mov_b32_e32 v1, v77
	v_mov_b32_e32 v2, v78
	v_mov_b32_e32 v3, v79
	v_lshlrev_b32_e32 v4, 16, v0
	v_and_b32_e32 v5, 0xffff0000, v0
	ds_bpermute_b32 v6, v52, v4
	ds_bpermute_b32 v7, v52, v5
	v_lshlrev_b32_e32 v0, 16, v1
	v_and_b32_e32 v1, 0xffff0000, v1
	s_waitcnt lgkmcnt(0)
	v_pk_mul_f32 v[6:7], v[40:41], v[6:7]
	s_nop 0
	v_pk_fma_f32 v[42:43], v[36:37], v[4:5], v[6:7]
	v_pk_fma_f32 v[4:5], v[36:37], v[4:5], v[6:7] neg_lo:[0,0,1] neg_hi:[0,0,1]
	s_nop 0
	v_cndmask_b32_e64 v43, v43, v5, s[0:1]
	v_cndmask_b32_e64 v42, v42, v4, s[0:1]
	ds_bpermute_b32 v4, v52, v0
	ds_bpermute_b32 v5, v52, v1
	s_waitcnt lgkmcnt(0)
	v_pk_mul_f32 v[4:5], v[34:35], v[4:5]
	s_nop 0
	v_pk_fma_f32 v[6:7], v[32:33], v[0:1], v[4:5]
	v_pk_fma_f32 v[0:1], v[32:33], v[0:1], v[4:5] neg_lo:[0,0,1] neg_hi:[0,0,1]
	s_nop 0
	v_cndmask_b32_e64 v45, v7, v1, s[0:1]
	v_cndmask_b32_e64 v44, v6, v0, s[0:1]
	v_lshlrev_b32_e32 v0, 16, v2
	v_and_b32_e32 v1, 0xffff0000, v2
	ds_bpermute_b32 v4, v52, v0
	ds_bpermute_b32 v5, v52, v1
	s_waitcnt lgkmcnt(0)
	v_pk_mul_f32 v[4:5], v[30:31], v[4:5]
	s_nop 0
	v_pk_fma_f32 v[6:7], v[28:29], v[0:1], v[4:5]
	v_pk_fma_f32 v[0:1], v[28:29], v[0:1], v[4:5] neg_lo:[0,0,1] neg_hi:[0,0,1]
	s_nop 0
	v_cndmask_b32_e64 v47, v7, v1, s[0:1]
	v_cndmask_b32_e64 v46, v6, v0, s[0:1]
	v_lshlrev_b32_e32 v0, 16, v3
	v_and_b32_e32 v1, 0xffff0000, v3
	ds_bpermute_b32 v2, v52, v0
	ds_bpermute_b32 v3, v52, v1
	s_waitcnt lgkmcnt(0)
	v_pk_mul_f32 v[2:3], v[26:27], v[2:3]
	s_nop 0
	v_pk_fma_f32 v[4:5], v[24:25], v[0:1], v[2:3]
	v_pk_fma_f32 v[0:1], v[24:25], v[0:1], v[2:3] neg_lo:[0,0,1] neg_hi:[0,0,1]
	v_cvt_pk_bf16_f32 v2, v46, v47
	v_cndmask_b32_e64 v49, v5, v1, s[0:1]
	v_cndmask_b32_e64 v48, v4, v0, s[0:1]
	v_lshl_add_u64 v[4:5], s[52:53], 0, v[12:13]
	v_add_co_u32_e32 v0, vcc, s3, v4
	v_cvt_pk_bf16_f32 v3, v48, v49
	s_nop 0
	v_addc_co_u32_e32 v1, vcc, 0, v5, vcc
	global_store_dwordx4 v[0:1], v[42:45], off nt
	global_store_dwordx4 v[0:1], v[46:49], off offset:16 nt
	v_cvt_pk_bf16_f32 v0, v42, v43
	v_cvt_pk_bf16_f32 v1, v44, v45
	s_and_b64 vcc, exec, s[14:15]
	s_cbranch_vccz .LBB0_517
	s_add_i32 s3, s60, 0xffff8000
	s_lshr_b32 s3, s3, 4
	s_mul_hi_u32 s5, s3, 0x440
	s_mulk_i32 s3, 0x440
	s_or_b32 s4, s3, s70
	s_lshl_b64 s[4:5], s[4:5], 10
	v_lshl_add_u64 v[6:7], v[8:9], 0, s[4:5]
	v_add_co_u32_e32 v6, vcc, 0x100000, v6
	s_mov_b64 s[12:13], 0
	s_nop 0
	v_addc_co_u32_e32 v7, vcc, 0, v7, vcc
	global_store_dwordx4 v[6:7], v[0:3], off

; __device__ __forceinline__ float bf2f(unsigned h) { return __uint_as_float(h << 16); }
; __global__ void __launch_bounds__(512, 2) fwd_kernel(Params P) {
;     ...
;             { const u32x4 raw = *(const u32x4*)(pr + 1024 + lane * 8); float x[8];
; #pragma unroll
;               for (int i = 0; i < 4; ++i) { x[2 * i] = bf2f(raw[i] & 0xffff); x[2 * i + 1] = bf2f(raw[i] >> 16); }
;               float* fo = OUT + O_AV + (size_t)row * 512 + lane * 8; __builtin_nontemporal_store((f32x4){x[0], x[1], x[2], x[3]}, (f32x4*)fo); __builtin_nontemporal_store((f32x4){x[4], x[5], x[6], x[7]}, (f32x4*)(fo + 4));
;               if (row >= NP) { const int bs = (row - NP) >> 4, t = (row - NP) & 15; *(u32x4*)(VAS + ((size_t)bs * LKSP + 1024 + t) * 512 + lane * 8) = raw; } }
.LBB0_519:
	v_add_co_u32_e32 v46, vcc, 0xc0c0000, v4
	s_cmp_lt_i32 s60, 0x8000
	s_nop 0
	v_addc_co_u32_e32 v47, vcc, 0, v5, vcc
	s_waitcnt vmcnt(7)
	s_nop 1
	v_mov_b32_e32 v0, v82
	v_mov_b32_e32 v1, v83
	v_mov_b32_e32 v2, v84
	v_mov_b32_e32 v3, v85
	v_lshlrev_b32_e32 v4, 16, v0
	v_and_b32_e32 v5, 0xffff0000, v0
	v_lshlrev_b32_e32 v6, 16, v1
	v_and_b32_e32 v7, 0xffff0000, v1
	v_lshlrev_b32_e32 v42, 16, v2
	v_and_b32_e32 v43, 0xffff0000, v2
	v_lshlrev_b32_e32 v44, 16, v3
	v_and_b32_e32 v45, 0xffff0000, v3
	global_store_dwordx4 v[46:47], v[4:7], off nt
	global_store_dwordx4 v[46:47], v[42:45], off offset:16 nt
	s_cbranch_scc1 .LBB0_521
	s_add_i32 s3, s60, 0xffff8000
	s_lshr_b32 s3, s3, 4
	s_mul_hi_u32 s5, s3, 0x440
	s_mulk_i32 s3, 0x440
	s_or_b32 s4, s3, s70
	s_lshl_b64 s[4:5], s[4:5], 10
	v_lshl_add_u64 v[4:5], v[10:11], 0, s[4:5]
	v_add_co_u32_e32 v4, vcc, 0x100000, v4
	s_nop 1
	v_addc_co_u32_e32 v5, vcc, 0, v5, vcc
	global_store_dwordx4 v[4:5], v[0:3], off

; __device__ __forceinline__ float bf2f(unsigned h) { return __uint_as_float(h << 16); }
; __device__ __forceinline__ unsigned pk2(float lo, float hi) { f32x2 v = {lo, hi}; bf16x2_t b = __builtin_convertvector(v, bf16x2_t); return __builtin_bit_cast(unsigned, b); }
; __global__ void __launch_bounds__(512, 2) fwd_kernel(Params P) {
;     ...
;             { float x[8]; u32x4 raw = (u32x4){0u, 0u, 0u, 0u}; if (lane < 48) raw = *(const u32x4*)(pr + 1536 + lane * 8);
;               float ss = 0.f;
; #pragma unroll
;               for (int i = 0; i < 4; ++i) { x[2 * i] = bf2f(raw[i] & 0xffff); x[2 * i + 1] = bf2f(raw[i] >> 16); ss += x[2 * i] * x[2 * i] + x[2 * i + 1] * x[2 * i + 1]; }
;               const float rstd = 1.0f / sqrtf(wave_sum(ss) * (1.0f / 384.0f) + EPS);
;               if (lane < 48) { const f32x4 g0 = *(const f32x4*)(qng + lane * 8), g1 = *(const f32x4*)(qng + lane * 8 + 4);
;                   u32x4 wv; wv.x = pk2(x[0] * rstd * g0[0], x[1] * rstd * g0[1]); wv.y = pk2(x[2] * rstd * g0[2], x[3] * rstd * g0[3]);
;                   wv.z = pk2(x[4] * rstd * g1[0], x[5] * rstd * g1[1]); wv.w = pk2(x[6] * rstd * g1[2], x[7] * rstd * g1[3]); *(u32x4*)(pr + 1536 + lane * 8) = wv; } }
.LBB0_523:
	s_or_b64 exec, exec, s[12:13]
	s_waitcnt vmcnt(8)
	s_nop 1
	v_mov_b32_e32 v0, v86
	v_mov_b32_e32 v1, v87
	v_mov_b32_e32 v2, v88
	v_mov_b32_e32 v3, v89
	v_lshlrev_b32_e32 v4, 16, v0
	v_and_b32_e32 v5, 0xffff0000, v0
	v_lshlrev_b32_e32 v6, 16, v1
	v_and_b32_e32 v7, 0xffff0000, v1
	v_pk_mul_f32 v[42:43], v[4:5], v[4:5]
	v_pk_mul_f32 v[44:45], v[6:7], v[6:7]
	v_lshlrev_b32_e32 v0, 16, v2
	v_and_b32_e32 v1, 0xffff0000, v2
	v_pk_mul_f32 v[46:47], v[0:1], v[0:1]
	v_lshlrev_b32_e32 v2, 16, v3
	v_and_b32_e32 v3, 0xffff0000, v3
	v_add_f32_e32 v37, v45, v44
	v_add_f32_e32 v41, v43, v42
	v_pk_mul_f32 v[48:49], v[2:3], v[2:3]
	v_add_f32_e32 v37, v41, v37
	v_add_f32_e32 v41, v47, v46
	v_add_f32_e32 v37, v37, v41
	v_add_f32_e32 v41, v49, v48
	v_add_f32_e32 v37, v37, v41
	ds_bpermute_b32 v41, v53, v37
	s_waitcnt lgkmcnt(0)
	v_add_f32_e32 v37, v37, v41
	ds_bpermute_b32 v41, v54, v37
	s_waitcnt lgkmcnt(0)
	v_add_f32_e32 v37, v37, v41
	ds_bpermute_b32 v41, v52, v37
	s_waitcnt lgkmcnt(0)
	v_add_f32_e32 v37, v37, v41
	ds_bpermute_b32 v41, v55, v37
	s_waitcnt lgkmcnt(0)
	v_add_f32_e32 v37, v37, v41
	ds_bpermute_b32 v41, v56, v37
	s_waitcnt lgkmcnt(0)
	v_add_f32_e32 v37, v37, v41
	ds_bpermute_b32 v41, v57, v37
	s_and_saveexec_b64 s[68:69], s[6:7]
	s_cbranch_execz .LBB0_525
	global_load_dwordx4 v[42:45], v[14:15], off
	global_load_dwordx4 v[46:49], v[14:15], off offset:16
	s_waitcnt lgkmcnt(0)
	v_add_f32_e32 v37, v37, v41
	v_fmamk_f32 v37, v37, 0x3b2aaaab, v66
	v_mul_f32_e32 v41, 0x4f800000, v37
	v_cmp_gt_f32_e32 vcc, s59, v37
	s_nop 1
	v_cndmask_b32_e32 v37, v37, v41, vcc
	v_sqrt_f32_e32 v41, v37
	s_nop 0
	v_add_u32_e32 v50, -1, v41
	v_add_u32_e32 v51, 1, v41
	v_fma_f32 v68, -v50, v41, v37
	v_fma_f32 v69, -v51, v41, v37
	v_cmp_ge_f32_e64 s[12:13], 0, v68
	s_nop 1
	v_cndmask_b32_e64 v41, v41, v50, s[12:13]
	v_cmp_lt_f32_e64 s[12:13], 0, v69
	s_nop 1
	v_cndmask_b32_e64 v41, v41, v51, s[12:13]
	v_mul_f32_e32 v50, 0x37800000, v41
	v_cndmask_b32_e32 v41, v41, v50, vcc
	v_cmp_class_f32_e32 vcc, v37, v67
	s_nop 1
	v_cndmask_b32_e32 v37, v41, v37, vcc
	v_div_scale_f32 v41, s[4:5], v37, v37, 1.0
	v_rcp_f32_e32 v50, v41
	v_div_scale_f32 v51, vcc, 1.0, v37, 1.0
	v_fma_f32 v68, -v41, v50, 1.0
	v_fmac_f32_e32 v50, v68, v50
	v_mul_f32_e32 v68, v51, v50
	v_fma_f32 v69, -v41, v68, v51
	v_fmac_f32_e32 v68, v69, v50
	v_fma_f32 v41, -v41, v68, v51
	v_div_fmas_f32 v41, v41, v50, v68
	v_div_fixup_f32 v50, v41, v37, 1.0
	v_pk_mul_f32 v[4:5], v[50:51], v[4:5] op_sel_hi:[0,1]
	v_pk_mul_f32 v[6:7], v[50:51], v[6:7] op_sel_hi:[0,1]
	v_pk_mul_f32 v[0:1], v[50:51], v[0:1] op_sel_hi:[0,1]
	v_pk_mul_f32 v[2:3], v[50:51], v[2:3] op_sel_hi:[0,1]
	s_waitcnt vmcnt(1)
	v_pk_mul_f32 v[4:5], v[4:5], v[42:43]
	v_pk_mul_f32 v[6:7], v[6:7], v[44:45]
	s_waitcnt vmcnt(0)
	v_pk_mul_f32 v[42:43], v[0:1], v[46:47]
	v_pk_mul_f32 v[44:45], v[2:3], v[48:49]
	v_cvt_pk_bf16_f32 v0, v4, v5
	v_cvt_pk_bf16_f32 v1, v6, v7
	v_cvt_pk_bf16_f32 v2, v42, v43
	v_cvt_pk_bf16_f32 v3, v44, v45
	global_store_dwordx4 v[22:23], v[0:3], off offset:3072

; __device__ __forceinline__ float bf2f(unsigned h) { return __uint_as_float(h << 16); }
; __device__ __forceinline__ unsigned pk2(float lo, float hi) { f32x2 v = {lo, hi}; bf16x2_t b = __builtin_convertvector(v, bf16x2_t); return __builtin_bit_cast(unsigned, b); }
; __global__ void __launch_bounds__(512, 2) fwd_kernel(Params P) {
;     ...
;             { float x[8]; u32x4 raw = (u32x4){0u, 0u, 0u, 0u}; if (lane < 32) raw = *(const u32x4*)(pr + 1920 + lane * 8);
;               float ss = 0.f;
; #pragma unroll
;               for (int i = 0; i < 4; ++i) { x[2 * i] = bf2f(raw[i] & 0xffff); x[2 * i + 1] = bf2f(raw[i] >> 16); ss += x[2 * i] * x[2 * i] + x[2 * i + 1] * x[2 * i + 1]; }
;               const float rstd = 1.0f / sqrtf(wave_sum(ss) * (1.0f / 256.0f) + EPS);
;               if (lane < 32) { const f32x4 g0 = *(const f32x4*)(kvg + lane * 8), g1 = *(const f32x4*)(kvg + lane * 8 + 4);
;                   float y[8];
; #pragma unroll
;                   for (int i = 0; i < 4; ++i) { y[i] = x[i] * rstd * g0[i]; y[4 + i] = x[4 + i] * rstd * g1[i]; }
;                   float* fo = OUT + O_LAT + (size_t)row * 256 + lane * 8; __builtin_nontemporal_store((f32x4){y[0], y[1], y[2], y[3]}, (f32x4*)fo); __builtin_nontemporal_store((f32x4){y[4], y[5], y[6], y[7]}, (f32x4*)(fo + 4));
;                   const size_t lr = row < NP ? (size_t)row : (size_t)NP + (size_t)((row - NP) >> 4) * LKSP + 1024 + ((row - NP) & 15);
;                   u32x4 wv; wv.x = pk2(y[0], y[1]); wv.y = pk2(y[2], y[3]); wv.z = pk2(y[4], y[5]); wv.w = pk2(y[6], y[7]); *(u32x4*)(LAT + lr * 256 + lane * 8) = wv; } }
.LBB0_527:
	s_or_b64 exec, exec, s[12:13]
	s_waitcnt vmcnt(4)
	s_nop 1
	v_mov_b32_e32 v0, v90
	v_mov_b32_e32 v1, v91
	v_mov_b32_e32 v2, v92
	v_mov_b32_e32 v3, v93
	v_lshlrev_b32_e32 v4, 16, v0
	v_and_b32_e32 v5, 0xffff0000, v0
	v_lshlrev_b32_e32 v6, 16, v1
	v_and_b32_e32 v7, 0xffff0000, v1
	v_pk_mul_f32 v[42:43], v[4:5], v[4:5]
	v_pk_mul_f32 v[44:45], v[6:7], v[6:7]
	v_lshlrev_b32_e32 v0, 16, v2
	v_and_b32_e32 v1, 0xffff0000, v2
	v_pk_mul_f32 v[46:47], v[0:1], v[0:1]
	v_lshlrev_b32_e32 v2, 16, v3
	v_and_b32_e32 v3, 0xffff0000, v3
	v_add_f32_e32 v37, v44, v45
	s_waitcnt lgkmcnt(0)
	v_add_f32_e32 v41, v42, v43
	v_pk_mul_f32 v[48:49], v[2:3], v[2:3]
	v_add_f32_e32 v37, v41, v37
	v_add_f32_e32 v41, v46, v47
	v_add_f32_e32 v37, v37, v41
	v_add_f32_e32 v41, v48, v49
	v_add_f32_e32 v37, v37, v41
	ds_bpermute_b32 v41, v53, v37
	v_cndmask_b32_e64 v42, 0, 1, s[14:15]
	v_cmp_ne_u32_e64 s[12:13], 1, v42
	s_waitcnt lgkmcnt(0)
	v_add_f32_e32 v37, v37, v41
	ds_bpermute_b32 v41, v54, v37
	s_waitcnt lgkmcnt(0)
	v_add_f32_e32 v37, v37, v41
	ds_bpermute_b32 v41, v52, v37
	s_waitcnt lgkmcnt(0)
	v_add_f32_e32 v37, v37, v41
	ds_bpermute_b32 v41, v55, v37
	s_waitcnt lgkmcnt(0)
	v_add_f32_e32 v37, v37, v41
	ds_bpermute_b32 v41, v56, v37
	s_waitcnt lgkmcnt(0)
	v_add_f32_e32 v37, v37, v41
	ds_bpermute_b32 v41, v57, v37
	s_and_saveexec_b64 s[68:69], s[8:9]
	s_cbranch_execz .LBB0_531
	s_waitcnt lgkmcnt(0)
	v_add_f32_e32 v37, v37, v41
	v_fmamk_f32 v37, v37, 0x3b800000, v66
	v_cmp_gt_f32_e32 vcc, s59, v37
	v_mul_f32_e32 v41, 0x4f800000, v37
	s_nop 0
	v_cndmask_b32_e32 v37, v37, v41, vcc
	v_sqrt_f32_e32 v41, v37
	s_nop 0
	v_add_u32_e32 v42, -1, v41
	v_fma_f32 v43, -v42, v41, v37
	v_cmp_ge_f32_e64 s[14:15], 0, v43
	v_add_u32_e32 v43, 1, v41
	s_nop 0
	v_cndmask_b32_e64 v42, v41, v42, s[14:15]
	v_fma_f32 v41, -v43, v41, v37
	v_cmp_lt_f32_e64 s[14:15], 0, v41
	s_nop 1
	v_cndmask_b32_e64 v41, v42, v43, s[14:15]
	v_mul_f32_e32 v42, 0x37800000, v41
	v_cndmask_b32_e32 v41, v41, v42, vcc
	v_cmp_class_f32_e32 vcc, v37, v67
	s_mov_b64 s[14:15], s[38:39]
	s_nop 0
	v_cndmask_b32_e32 v37, v41, v37, vcc
	v_div_scale_f32 v41, s[4:5], v37, v37, 1.0
	v_rcp_f32_e32 v42, v41
	s_nop 0
	v_fma_f32 v43, -v41, v42, 1.0
	v_fmac_f32_e32 v42, v43, v42
	v_div_scale_f32 v43, vcc, 1.0, v37, 1.0
	v_mul_f32_e32 v44, v43, v42
	v_fma_f32 v45, -v41, v44, v43
	v_fmac_f32_e32 v44, v45, v42
	v_fma_f32 v41, -v41, v44, v43
	v_div_fmas_f32 v41, v41, v42, v44
	global_load_dwordx4 v[42:45], v[16:17], off offset:16
	global_load_dwordx4 v[46:49], v[16:17], off
	v_div_fixup_f32 v50, v41, v37, 1.0
	v_pk_mul_f32 v[0:1], v[50:51], v[0:1] op_sel_hi:[0,1]
	v_pk_mul_f32 v[4:5], v[50:51], v[4:5] op_sel_hi:[0,1]
	v_pk_mul_f32 v[6:7], v[50:51], v[6:7] op_sel_hi:[0,1]
	v_pk_mul_f32 v[2:3], v[50:51], v[2:3] op_sel_hi:[0,1]
	s_waitcnt vmcnt(1)
	v_pk_mul_f32 v[0:1], v[42:43], v[0:1]
	v_lshl_add_u64 v[42:43], s[34:35], 0, v[12:13]
	v_add_co_u32_e32 v42, vcc, 0x10100000, v42
	s_waitcnt vmcnt(0)
	v_pk_mul_f32 v[4:5], v[46:47], v[4:5]
	v_addc_co_u32_e32 v43, vcc, 0, v43, vcc
	v_pk_mul_f32 v[6:7], v[48:49], v[6:7]
	v_pk_mul_f32 v[2:3], v[44:45], v[2:3]
	s_and_b64 vcc, exec, s[12:13]
	global_store_dwordx4 v[42:43], v[4:7], off nt
	global_store_dwordx4 v[42:43], v[0:3], off offset:16 nt
	s_cbranch_vccnz .LBB0_530
	s_add_i32 s3, s60, 0xffff8000
	s_lshr_b32 s3, s3, 4
	s_mul_hi_u32 s5, s3, 0x440
	s_mulk_i32 s3, 0x440
	s_or_b32 s4, s3, s70
	s_lshl_b64 s[4:5], s[4:5], 9
	s_add_u32 s14, s4, 0x1080000
	s_addc_u32 s15, s5, 0

; __device__ __forceinline__ float bf2f(unsigned h) { return __uint_as_float(h << 16); }
; __device__ __forceinline__ unsigned pk2(float lo, float hi) { f32x2 v = {lo, hi}; bf16x2_t b = __builtin_convertvector(v, bf16x2_t); return __builtin_bit_cast(unsigned, b); }
; __global__ void __launch_bounds__(512, 2) fwd_kernel(Params P) {
;     ...
;             { float x[8], y[8]; u32x4 raw = (u32x4){0u, 0u, 0u, 0u}; if (lane < 8) raw = *(const u32x4*)(pr + 2176 + lane * 8);
; #pragma unroll
;               for (int i = 0; i < 4; ++i) { x[2 * i] = bf2f(raw[i] & 0xffff); x[2 * i + 1] = bf2f(raw[i] >> 16); }
; #pragma unroll
;               for (int i = 0; i < 8; ++i) { const float o = __shfl_xor(x[i], 4); y[i] = ishi ? (x[i] * cs[i] + o * sn[i]) : (x[i] * cs[i] - o * sn[i]); }
;               if (lane < 8) { float* fo = OUT + O_KR + (size_t)row * 64 + lane * 8; __builtin_nontemporal_store((f32x4){y[0], y[1], y[2], y[3]}, (f32x4*)fo); __builtin_nontemporal_store((f32x4){y[4], y[5], y[6], y[7]}, (f32x4*)(fo + 4));
;                   const size_t lr = row < NP ? (size_t)row : (size_t)NP + (size_t)((row - NP) >> 4) * LKSP + 1024 + ((row - NP) & 15);
;                   u32x4 wv; wv.x = pk2(y[0], y[1]); wv.y = pk2(y[2], y[3]); wv.z = pk2(y[4], y[5]); wv.w = pk2(y[6], y[7]); *(u32x4*)(KR + lr * 64 + lane * 8) = wv; } }
.LBB0_533:
	s_or_b64 exec, exec, s[14:15]
	s_waitcnt vmcnt(6)
	s_nop 1
	v_mov_b32_e32 v0, v94
	v_mov_b32_e32 v1, v95
	v_mov_b32_e32 v2, v96
	v_mov_b32_e32 v3, v97
	v_lshlrev_b32_e32 v37, 16, v0
	v_and_b32_e32 v50, 0xffff0000, v0
	v_lshlrev_b32_e32 v46, 16, v1
	v_and_b32_e32 v47, 0xffff0000, v1
	v_lshlrev_b32_e32 v4, 16, v2
	v_and_b32_e32 v5, 0xffff0000, v2
	v_lshlrev_b32_e32 v6, 16, v3
	v_and_b32_e32 v7, 0xffff0000, v3
	ds_bpermute_b32 v0, v52, v37
	ds_bpermute_b32 v51, v52, v50
	ds_bpermute_b32 v48, v52, v46
	ds_bpermute_b32 v49, v52, v47
	ds_bpermute_b32 v44, v52, v4
	ds_bpermute_b32 v45, v52, v5
	ds_bpermute_b32 v42, v52, v6
	ds_bpermute_b32 v43, v52, v7
	s_and_saveexec_b64 s[14:15], s[10:11]
	s_cbranch_execz .LBB0_514
	s_waitcnt lgkmcnt(6)
	v_pk_mul_f32 v[2:3], v[38:39], v[50:51]
	s_waitcnt lgkmcnt(2)
	v_pk_mul_f32 v[30:31], v[30:31], v[44:45]
	v_add_f32_e32 v1, v2, v3
	v_sub_f32_e32 v2, v2, v3
	v_cndmask_b32_e64 v1, v1, v2, s[0:1]
	v_pk_mul_f32 v[2:3], v[34:35], v[48:49]
	s_waitcnt lgkmcnt(0)
	v_pk_mul_f32 v[26:27], v[26:27], v[42:43]
	v_pk_fma_f32 v[34:35], v[32:33], v[46:47], v[2:3]
	v_pk_fma_f32 v[2:3], v[32:33], v[46:47], v[2:3] neg_lo:[0,0,1] neg_hi:[0,0,1]
	v_pk_fma_f32 v[32:33], v[28:29], v[4:5], v[30:31]
	v_pk_fma_f32 v[4:5], v[28:29], v[4:5], v[30:31] neg_lo:[0,0,1] neg_hi:[0,0,1]
	v_pk_fma_f32 v[28:29], v[24:25], v[6:7], v[26:27]
	v_pk_fma_f32 v[6:7], v[24:25], v[6:7], v[26:27] neg_lo:[0,0,1] neg_hi:[0,0,1]
	v_lshl_add_u64 v[24:25], s[16:17], 0, v[12:13]
	v_mul_f32_e32 v0, v40, v0
	v_add_co_u32_e32 v24, vcc, 0x12120000, v24
	v_cndmask_b32_e64 v0, v0, -v0, s[0:1]
	s_nop 0
	v_addc_co_u32_e32 v25, vcc, 0, v25, vcc
	v_fmac_f32_e32 v0, v36, v37
	v_cndmask_b32_e64 v3, v35, v3, s[0:1]
	v_cndmask_b32_e64 v2, v34, v2, s[0:1]
	v_cndmask_b32_e64 v5, v33, v5, s[0:1]
	v_cndmask_b32_e64 v4, v32, v4, s[0:1]
	v_cndmask_b32_e64 v7, v29, v7, s[0:1]
	v_cndmask_b32_e64 v6, v28, v6, s[0:1]
	s_and_b64 vcc, exec, s[12:13]
	s_mov_b64 s[12:13], s[60:61]
	global_store_dwordx4 v[24:25], v[0:3], off nt
	global_store_dwordx4 v[24:25], v[4:7], off offset:16 nt
	s_cbranch_vccnz .LBB0_513
	s_add_i32 s3, s60, 0xffff8000
	s_lshr_b32 s3, s3, 4
	s_mul_hi_u32 s4, s3, 0x440
	s_mulk_i32 s3, 0x440
	s_or_b32 s3, s3, s70
	s_add_u32 s12, s3, 0x8400
	s_addc_u32 s13, s4, 0
	s_branch .LBB0_513
